# P1/P6 peeled first K-iteration: first two counted vmcnt waits relaxed to 16 so they do not wait for the epilogue's store acks; pre-loop prologue waits vmcnt(0)
# baseline (speedup 1.0000x reference)
; #define PG8_STAGE(bufoff, gbase, voff) do { _Pragma("unroll") for (int _i = 0; _i < 2; ++_i) \
;         __builtin_amdgcn_global_load_lds((const unsigned*)((const char*)(gbase) + (voff)[_i]), (PG8_LAS unsigned*)(lds + (bufoff) + ldsw + _i * 8192), 16, 0, 0); } while (0)
; #define PG8_WAIT_V(n) asm volatile("s_waitcnt vmcnt(" #n ")" ::: "memory")
; #define PG8_BAR __builtin_amdgcn_s_barrier()
; template <class Epi, class Sched, bool ALIGN_EPI = false, bool SP2 = false>
; __device__ __forceinline__ void gemm_phase(PG8_LAS unsigned char* lds, const Gemm g, const Sched& S, const Epi& E) {
;     ...
;     const int wid = __builtin_amdgcn_readfirstlane(tid >> 6), lane = tid & 63, wr = wid >> 2, wc = wid & 3, fr = lane & 15, fq = lane >> 4;
;     const int K = g.K, nt = K / BK;
;     unsigned voffA[2], voffB[2];
; #pragma unroll
;     for (int i = 0; i < 2; ++i) { int R, C; stage_rc(tid * 16 + i * 8192, R, C); const int Rb = Epi::PERM ? ((R & ~31) + perm32(R & 31)) : R;
;         voffA[i] = (unsigned)(R * K + C) * 2u; voffB[i] = (unsigned)(Rb * K + C) * 2u; }
;     const size_t kstep = (size_t)(BK * 2);
;     const size_t hstep = (size_t)HALF * K * 2;
;     const size_t tstep = 2 * hstep;
;     const unsigned ldsw = (unsigned)wid * 1024u;
;     const int aoff = lds_byte(wr * 64 + fr, fq * 8), boff = lds_byte(wc * 32 + fr, fq * 8);
;     ...
;         PG8_STAGE(PG8_SB(0, 0), cB, voffB); PG8_STAGE(PG8_SB(0, 1), cB + hstep, voffB); PG8_STAGE(PG8_SA(0, 0), cA, voffA); PG8_STAGE(PG8_SA(0, 1), cA + hstep, voffA);
;         if (wr == 1) PG8_BAR;
;         PG8_WAIT_V(2); PG8_BAR;
;         PG8_STAGE(PG8_SB(1, 0), cB + kstep, voffB); PG8_STAGE(PG8_SA(1, 0), cA + kstep, voffA); PG8_STAGE(PG8_SB(1, 1), cB + hstep + kstep, voffB);
;         PG8_WAIT_V(6); PG8_BAR;
.LBB0_186:
	s_lshl_b32 s4, s4, 5
	s_and_b32 s14, s4, 0x60
	s_mov_b64 s[4:5], 0x80
	s_add_i32 m0, s21, 0x18000
	v_lshl_add_u64 v[6:7], v[6:7], 0, s[4:5]
	s_lshl_b32 s7, s6, 13
	s_lshl_b32 s15, s14, 7
	s_waitcnt vmcnt(2)
	s_barrier
	global_load_lds_dwordx4 v[6:7], off
	v_lshl_add_u64 v[4:5], v[4:5], 0, s[4:5]
	s_add_i32 m0, s21, 0x1a000
	s_add_i32 s42, s21, 0x8000
	s_add_i32 s43, s21, 0xa000
	global_load_lds_dwordx4 v[4:5], off
	v_lshl_add_u64 v[0:1], v[0:1], 0, s[4:5]
	s_mov_b32 m0, s42
	s_add_u32 s8, s24, 0x40080
	global_load_lds_dwordx4 v[0:1], off
	v_lshl_add_u64 v[0:1], v[2:3], 0, s[4:5]
	s_mov_b32 m0, s43
	s_addc_u32 s9, s25, 0
	global_load_lds_dwordx4 v[0:1], off
	s_add_i32 m0, s21, 0x1c000
	v_lshl_add_u64 v[0:1], s[8:9], 0, v[132:133]
	global_load_lds_dwordx4 v[0:1], off
	v_lshl_add_u64 v[0:1], s[8:9], 0, v[128:129]
	s_add_i32 m0, s21, 0x1e000
	s_cmpk_lt_u32 s1, 0x100
	global_load_lds_dwordx4 v[0:1], off
	v_lshrrev_b32_e32 v1, 1, v9
	v_and_b32_e32 v1, 24, v1
	v_and_b32_e32 v0, 15, v9
	v_lshlrev_b32_e32 v2, 1, v1
	v_lshl_or_b32 v144, s6, 6, v0
	v_lshl_or_b32 v0, v0, 6, v2
	v_lshlrev_b32_e32 v2, 2, v9
	v_and_b32_e32 v2, 32, v2
	v_bitop3_b32 v3, v0, s7, v2 bitop3:0xde
	v_bitop3_b32 v145, v0, s15, v2 bitop3:0xde
	v_lshlrev_b32_e32 v0, 14, v13
	v_and_b32_e32 v0, 0xffff8000, v0
	v_or_b32_e32 v146, s14, v1
	v_lshl_add_u32 v0, v12, 11, v0
	v_and_b32_e32 v1, 1, v13
	v_lshl_or_b32 v0, v1, 6, v0
	v_lshl_add_u32 v136, v14, 1, v0
	v_lshlrev_b32_e32 v0, 14, v8
	v_and_b32_e32 v0, 0xffff8000, v0
	s_waitcnt vmcnt(0)
	v_lshl_add_u32 v0, v10, 11, v0
	v_and_b32_e32 v1, 1, v8
	s_sext_i32_i8 s49, s0
	s_cselect_b64 s[6:7], -1, 0
	v_readlane_b32 s0, v235, 6
	v_lshl_or_b32 v0, v1, 6, v0
	s_add_i32 s46, 0, 0x10000
	s_add_i32 s47, 0, 0x14000
	s_ashr_i32 s44, s0, 31
	s_mov_b32 s45, s0
	v_mov_b32_e32 v137, v133
	v_lshl_add_u32 v138, v11, 1, v0
	v_mov_b32_e32 v139, v133
	v_mov_b64_e32 v[140:141], 0xb00
	v_mov_b64_e32 v[142:143], 0xaff
	v_add_u32_e32 v147, s46, v145
	v_add_u32_e32 v148, s47, v145
	v_add_u32_e32 v149, 0, v3
	s_movk_i32 s48, 0x1600
	s_barrier
	v_readlane_b32 s1, v235, 7
	s_branch .LBB0_189

; #define PG8_STAGE(bufoff, gbase, voff) do { _Pragma("unroll") for (int _i = 0; _i < 2; ++_i) \
;         __builtin_amdgcn_global_load_lds((const unsigned*)((const char*)(gbase) + (voff)[_i]), (PG8_LAS unsigned*)(lds + (bufoff) + ldsw + _i * 8192), 16, 0, 0); } while (0)
; #define PG8_LDA(dst, b, h) do { _Pragma("unroll") for (int m = 0; m < 4; ++m) _Pragma("unroll") for (int k = 0; k < 2; ++k) dst[m][k] = *(const PG8_LAS bf16x8*)(lds + PG8_SA(b, h) + aoff + m * 2048 + k * 1024); } while (0)
; #define PG8_LDB(dst, b, h) do { _Pragma("unroll") for (int n = 0; n < 2; ++n) _Pragma("unroll") for (int k = 0; k < 2; ++k) dst[n][k] = *(const PG8_LAS bf16x8*)(lds + PG8_SB(b, h) + boff + n * 2048 + k * 1024); } while (0)
; #define PG8_WAIT_V(n) asm volatile("s_waitcnt vmcnt(" #n ")" ::: "memory")
; #define PG8_WAIT_L(n) asm volatile("s_waitcnt lgkmcnt(" #n ")" ::: "memory")
; #define PG8_BAR __builtin_amdgcn_s_barrier()
; #define PG8_SCHED __builtin_amdgcn_sched_barrier(0)
; template <class Epi, class Sched, bool ALIGN_EPI = false, bool SP2 = false>
; __device__ __forceinline__ void gemm_phase(PG8_LAS unsigned char* lds, const Gemm g, const Sched& S, const Epi& E) {
;     ...
;         const bool has_next = S.next(ui + 1, nxt);
;         const char* nA = has_next ? (const char*)g.A + (size_t)nxt.pm * tstep : cA; const char* nB = has_next ? (const char*)g.Bt + (size_t)nxt.pn * tstep : cB;
;         for (int t = 0; t < nt; t += 2) {
;             const bool last = (t == nt - 2);
;             const char* a1 = cA + (size_t)(t + 1) * kstep;
;             const char* a2 = last ? nA : cA + (size_t)(t + 2) * kstep; const char* b2 = last ? nB : cB + (size_t)(t + 2) * kstep;
;             const char* a3 = a2 + kstep; const char* b3 = b2 + kstep;
;             if (last && has_next) S.a_ready(nxt);
;             if constexpr (SP2) {
;             PG8_LDB(B0, 0, 0); PG8_LDB(B1, 0, 1); PG8_SCHED; PG8_LDA(At, 0, 0); PG8_STAGE(PG8_SA(1, 1), a1 + hstep, voffA);
;             PG8_WAIT_V(8); PG8_WAIT_L(0); PG8_BAR; PG8_MMA(0, 0, At, B0); PG8_MMA(0, 1, At, B1); PG8_BAR; PG8_SCHED;
;             PG8_LDA(At, 0, 1); PG8_STAGE(PG8_SB(0, 0), b2, voffB); PG8_STAGE(PG8_SB(0, 1), b2 + hstep, voffB); PG8_STAGE(PG8_SA(0, 0), a2, voffA);
;             PG8_WAIT_V(8); PG8_WAIT_L(0); PG8_BAR; PG8_MMA(1, 0, At, B0); PG8_MMA(1, 1, At, B1); PG8_BAR; PG8_SCHED;
.LBB0_191:
	s_ashr_i32 s15, s14, 31
	s_lshl_b64 s[16:17], s[14:15], 19
	v_readlane_b32 s18, v235, 31
	v_readlane_b32 s19, v235, 32
	s_add_u32 s16, s18, s16
	s_addc_u32 s17, s19, s17
	s_and_b64 s[18:19], s[0:1], exec
	s_cselect_b32 s15, s17, s23
	s_cselect_b32 s50, s16, s22
	s_ashr_i32 s9, s8, 31
	s_lshl_b64 s[18:19], s[8:9], 19
	s_add_u32 s18, s33, s18
	s_addc_u32 s19, s34, s19
	s_and_b64 s[30:31], s[0:1], exec
	s_cselect_b32 s9, s19, s25
	s_cselect_b32 s51, s18, s24
	s_add_u32 s22, s22, 0x40080
	s_addc_u32 s23, s23, 0
	s_add_u32 s52, s24, 0x100
	s_addc_u32 s53, s25, 0
	s_mov_b32 s54, -2
	ds_read_b128 v[150:153], v147
	ds_read_b128 v[154:157], v147 offset:1024
	ds_read_b128 v[158:161], v147 offset:2048
	ds_read_b128 v[162:165], v147 offset:3072
	ds_read_b128 v[166:169], v148
	ds_read_b128 v[170:173], v148 offset:1024
	ds_read_b128 v[174:177], v148 offset:2048
	ds_read_b128 v[178:181], v148 offset:3072
	s_add_u32 s24, s22, 0xfffc0080
	s_addc_u32 s25, s23, -1
	s_cmp_eq_u32 s54, 12
	s_cselect_b32 s31, s15, s25
	s_cselect_b32 s30, s50, s24
	s_cselect_b32 s25, s9, s53
	s_cselect_b32 s24, s51, s52
	v_lshl_add_u64 v[186:187], s[22:23], 0, v[136:137]
	s_add_i32 m0, s21, 0xc000
	ds_read_b128 v[182:185], v149
	ds_read_b128 v[192:195], v149 offset:1024
	ds_read_b128 v[196:199], v149 offset:2048
	ds_read_b128 v[200:203], v149 offset:3072
	ds_read_b128 v[204:207], v149 offset:4096
	ds_read_b128 v[208:211], v149 offset:5120
	ds_read_b128 v[212:215], v149 offset:6144
	ds_read_b128 v[216:219], v149 offset:7168
	global_load_lds_dwordx4 v[186:187], off
	v_lshl_add_u64 v[186:187], s[22:23], 0, v[138:139]
	s_add_i32 m0, s21, 0xe000
	s_nop 0
	global_load_lds_dwordx4 v[186:187], off
	s_waitcnt vmcnt(16)
	s_waitcnt lgkmcnt(0)
	s_barrier
	s_setprio 1
	v_mfma_f32_16x16x32_bf16 v[124:127], v[150:153], v[182:185], 0
	v_mfma_f32_16x16x32_bf16 v[120:123], v[158:161], v[182:185], 0
	v_mfma_f32_16x16x32_bf16 v[108:111], v[150:153], v[196:199], 0
	v_mfma_f32_16x16x32_bf16 v[104:107], v[158:161], v[196:199], 0
	v_mfma_f32_16x16x32_bf16 v[92:95], v[150:153], v[204:207], 0
	v_mfma_f32_16x16x32_bf16 v[88:91], v[158:161], v[204:207], 0
	v_mfma_f32_16x16x32_bf16 v[76:79], v[150:153], v[212:215], 0
	v_mfma_f32_16x16x32_bf16 v[72:75], v[158:161], v[212:215], 0
	v_mfma_f32_16x16x32_bf16 v[124:127], v[154:157], v[192:195], v[124:127]
	v_mfma_f32_16x16x32_bf16 v[120:123], v[162:165], v[192:195], v[120:123]
	v_mfma_f32_16x16x32_bf16 v[108:111], v[154:157], v[200:203], v[108:111]
	v_mfma_f32_16x16x32_bf16 v[104:107], v[162:165], v[200:203], v[104:107]
	v_mfma_f32_16x16x32_bf16 v[92:95], v[154:157], v[208:211], v[92:95]
	v_mfma_f32_16x16x32_bf16 v[88:91], v[162:165], v[208:211], v[88:91]
	v_mfma_f32_16x16x32_bf16 v[76:79], v[154:157], v[216:219], v[76:79]
	v_mfma_f32_16x16x32_bf16 v[72:75], v[162:165], v[216:219], v[72:75]
	v_mfma_f32_16x16x32_bf16 v[116:119], v[166:169], v[182:185], 0
	v_mfma_f32_16x16x32_bf16 v[112:115], v[174:177], v[182:185], 0
	v_mfma_f32_16x16x32_bf16 v[100:103], v[166:169], v[196:199], 0
	v_mfma_f32_16x16x32_bf16 v[96:99], v[174:177], v[196:199], 0
	v_mfma_f32_16x16x32_bf16 v[84:87], v[166:169], v[204:207], 0
	v_mfma_f32_16x16x32_bf16 v[80:83], v[174:177], v[204:207], 0
	v_mfma_f32_16x16x32_bf16 v[68:71], v[166:169], v[212:215], 0
	v_mfma_f32_16x16x32_bf16 v[64:67], v[174:177], v[212:215], 0
	v_mfma_f32_16x16x32_bf16 v[116:119], v[170:173], v[192:195], v[116:119]
	v_mfma_f32_16x16x32_bf16 v[112:115], v[178:181], v[192:195], v[112:115]
	v_mfma_f32_16x16x32_bf16 v[100:103], v[170:173], v[200:203], v[100:103]
	v_mfma_f32_16x16x32_bf16 v[96:99], v[178:181], v[200:203], v[96:99]
	v_mfma_f32_16x16x32_bf16 v[84:87], v[170:173], v[208:211], v[84:87]
	v_mfma_f32_16x16x32_bf16 v[80:83], v[178:181], v[208:211], v[80:83]
	v_mfma_f32_16x16x32_bf16 v[68:71], v[170:173], v[216:219], v[68:71]
	v_mfma_f32_16x16x32_bf16 v[64:67], v[178:181], v[216:219], v[64:67]
	s_setprio 0
	s_barrier
	s_add_i32 s55, s46, s35
	v_lshl_add_u64 v[186:187], s[24:25], 0, v[132:133]
	s_mov_b32 m0, s55
	ds_read_b128 v[182:185], v149 offset:16384
	ds_read_b128 v[192:195], v149 offset:17408
	ds_read_b128 v[196:199], v149 offset:18432
	ds_read_b128 v[200:203], v149 offset:19456
	ds_read_b128 v[204:207], v149 offset:20480
	ds_read_b128 v[208:211], v149 offset:21504
	ds_read_b128 v[212:215], v149 offset:22528
	ds_read_b128 v[216:219], v149 offset:23552
	global_load_lds_dwordx4 v[186:187], off
	s_add_i32 m0, s55, 0x2000
	s_add_u32 s56, s24, 0x40000
	v_lshl_add_u64 v[220:221], s[24:25], 0, v[128:129]
	s_addc_u32 s57, s25, 0
	s_add_i32 s55, s47, s35
	global_load_lds_dwordx4 v[220:221], off
	v_lshl_add_u64 v[222:223], s[56:57], 0, v[132:133]
	s_mov_b32 m0, s55
	v_lshl_add_u64 v[224:225], s[30:31], 0, v[130:131]
	global_load_lds_dwordx4 v[222:223], off
	v_lshl_add_u64 v[222:223], s[56:57], 0, v[128:129]
	s_add_i32 m0, s55, 0x2000
	s_nop 0
	global_load_lds_dwordx4 v[222:223], off
	v_lshl_add_u64 v[222:223], s[30:31], 0, v[134:135]
	s_mov_b32 m0, s21
	s_nop 0
	global_load_lds_dwordx4 v[222:223], off
	s_mov_b32 m0, s38
	s_nop 0
	global_load_lds_dwordx4 v[224:225], off
	s_waitcnt vmcnt(16)
	s_waitcnt lgkmcnt(0)
	s_barrier
; #define PG8_STAGE(bufoff, gbase, voff) do { _Pragma("unroll") for (int _i = 0; _i < 2; ++_i) \
;         __builtin_amdgcn_global_load_lds((const unsigned*)((const char*)(gbase) + (voff)[_i]), (PG8_LAS unsigned*)(lds + (bufoff) + ldsw + _i * 8192), 16, 0, 0); } while (0)
; #define PG8_LDA(dst, b, h) do { _Pragma("unroll") for (int m = 0; m < 4; ++m) _Pragma("unroll") for (int k = 0; k < 2; ++k) dst[m][k] = *(const PG8_LAS bf16x8*)(lds + PG8_SA(b, h) + aoff + m * 2048 + k * 1024); } while (0)
; #define PG8_LDB(dst, b, h) do { _Pragma("unroll") for (int n = 0; n < 2; ++n) _Pragma("unroll") for (int k = 0; k < 2; ++k) dst[n][k] = *(const PG8_LAS bf16x8*)(lds + PG8_SB(b, h) + boff + n * 2048 + k * 1024); } while (0)
; #define PG8_MMA(ai, bj, At, Bt) do { __builtin_amdgcn_s_setprio(1); _Pragma("unroll") for (int m = 0; m < 4; ++m) _Pragma("unroll") for (int n = 0; n < 2; ++n) _Pragma("unroll") for (int k = 0; k < 2; ++k) \
;         acc[ai][bj][m][n] = __builtin_amdgcn_mfma_f32_16x16x32_bf16(Bt[n][k], At[m][k], acc[ai][bj][m][n], 0, 0, 0); __builtin_amdgcn_s_setprio(0); } while (0)
; #define PG8_WAIT_V(n) asm volatile("s_waitcnt vmcnt(" #n ")" ::: "memory")
; #define PG8_WAIT_L(n) asm volatile("s_waitcnt lgkmcnt(" #n ")" ::: "memory")
; #define PG8_BAR __builtin_amdgcn_s_barrier()
; #define PG8_SCHED __builtin_amdgcn_sched_barrier(0)
; template <class Epi, class Sched, bool ALIGN_EPI = false, bool SP2 = false>
; __device__ __forceinline__ void gemm_phase(PG8_LAS unsigned char* lds, const Gemm g, const Sched& S, const Epi& E) {
;     ...
;             PG8_LDA(At, 0, 1); PG8_STAGE(PG8_SB(0, 0), b2, voffB); PG8_STAGE(PG8_SB(0, 1), b2 + hstep, voffB); PG8_STAGE(PG8_SA(0, 0), a2, voffA);
;             PG8_WAIT_V(8); PG8_WAIT_L(0); PG8_BAR; PG8_MMA(1, 0, At, B0); PG8_MMA(1, 1, At, B1); PG8_BAR; PG8_SCHED;
;             PG8_LDB(B0, 1, 0); PG8_LDB(B1, 1, 1); PG8_SCHED; PG8_LDA(At, 1, 0); PG8_STAGE(PG8_SA(0, 1), a2 + hstep, voffA);
;             PG8_WAIT_V(8); PG8_WAIT_L(0); PG8_BAR; PG8_MMA(0, 0, At, B0); PG8_MMA(0, 1, At, B1); PG8_BAR; PG8_SCHED;
	s_setprio 1
	v_mfma_f32_16x16x32_bf16 v[60:63], v[150:153], v[182:185], 0
	v_mfma_f32_16x16x32_bf16 v[56:59], v[158:161], v[182:185], 0
	v_mfma_f32_16x16x32_bf16 v[44:47], v[150:153], v[196:199], 0
	v_mfma_f32_16x16x32_bf16 v[40:43], v[158:161], v[196:199], 0
	v_mfma_f32_16x16x32_bf16 v[28:31], v[150:153], v[204:207], 0
	v_mfma_f32_16x16x32_bf16 v[24:27], v[158:161], v[204:207], 0
	v_mfma_f32_16x16x32_bf16 v[12:15], v[150:153], v[212:215], 0
	v_mfma_f32_16x16x32_bf16 v[8:11], v[158:161], v[212:215], 0
	v_mfma_f32_16x16x32_bf16 v[60:63], v[154:157], v[192:195], v[60:63]
	v_mfma_f32_16x16x32_bf16 v[56:59], v[162:165], v[192:195], v[56:59]
	v_mfma_f32_16x16x32_bf16 v[44:47], v[154:157], v[200:203], v[44:47]
	v_mfma_f32_16x16x32_bf16 v[40:43], v[162:165], v[200:203], v[40:43]
	v_mfma_f32_16x16x32_bf16 v[28:31], v[154:157], v[208:211], v[28:31]
	v_mfma_f32_16x16x32_bf16 v[24:27], v[162:165], v[208:211], v[24:27]
	v_mfma_f32_16x16x32_bf16 v[12:15], v[154:157], v[216:219], v[12:15]
	v_mfma_f32_16x16x32_bf16 v[8:11], v[162:165], v[216:219], v[8:11]
	v_mfma_f32_16x16x32_bf16 v[52:55], v[166:169], v[182:185], 0
	v_mfma_f32_16x16x32_bf16 v[48:51], v[174:177], v[182:185], 0
	v_mfma_f32_16x16x32_bf16 v[36:39], v[166:169], v[196:199], 0
	v_mfma_f32_16x16x32_bf16 v[32:35], v[174:177], v[196:199], 0
	v_mfma_f32_16x16x32_bf16 v[20:23], v[166:169], v[204:207], 0
	v_mfma_f32_16x16x32_bf16 v[16:19], v[174:177], v[204:207], 0
	v_mfma_f32_16x16x32_bf16 v[4:7], v[166:169], v[212:215], 0
	v_mfma_f32_16x16x32_bf16 v[0:3], v[174:177], v[212:215], 0
	v_mfma_f32_16x16x32_bf16 v[52:55], v[170:173], v[192:195], v[52:55]
	v_mfma_f32_16x16x32_bf16 v[48:51], v[178:181], v[192:195], v[48:51]
	v_mfma_f32_16x16x32_bf16 v[36:39], v[170:173], v[200:203], v[36:39]
	v_mfma_f32_16x16x32_bf16 v[32:35], v[178:181], v[200:203], v[32:35]
	v_mfma_f32_16x16x32_bf16 v[20:23], v[170:173], v[208:211], v[20:23]
	v_mfma_f32_16x16x32_bf16 v[16:19], v[178:181], v[208:211], v[16:19]
	v_mfma_f32_16x16x32_bf16 v[4:7], v[170:173], v[216:219], v[4:7]
	v_mfma_f32_16x16x32_bf16 v[0:3], v[178:181], v[216:219], v[0:3]
	s_setprio 0
	s_barrier
	s_add_i32 s55, 0, 0x18000
	s_add_i32 s56, 0, 0x1c000
	v_add_u32_e32 v162, s55, v145
	v_add_u32_e32 v178, s56, v145
	ds_read_b128 v[150:153], v162
	ds_read_b128 v[154:157], v162 offset:1024
	ds_read_b128 v[158:161], v162 offset:2048
	ds_read_b128 v[162:165], v162 offset:3072
	ds_read_b128 v[166:169], v178
	ds_read_b128 v[170:173], v178 offset:1024
	ds_read_b128 v[174:177], v178 offset:2048
	ds_read_b128 v[178:181], v178 offset:3072
	s_add_u32 s30, s30, 0x40000
	s_addc_u32 s31, s31, 0
	s_mov_b32 m0, s39
	v_lshl_add_u64 v[226:227], s[30:31], 0, v[134:135]
	ds_read_b128 v[182:185], v149 offset:32768
	ds_read_b128 v[192:195], v149 offset:33792
	ds_read_b128 v[196:199], v149 offset:34816
	ds_read_b128 v[200:203], v149 offset:35840
	ds_read_b128 v[204:207], v149 offset:36864
	ds_read_b128 v[208:211], v149 offset:37888
	ds_read_b128 v[212:215], v149 offset:38912
	ds_read_b128 v[216:219], v149 offset:39936
	global_load_lds_dwordx4 v[226:227], off
	v_lshl_add_u64 v[226:227], s[30:31], 0, v[130:131]
	s_mov_b32 m0, s40
	s_nop 0
	global_load_lds_dwordx4 v[226:227], off
	s_waitcnt vmcnt(8)
	s_waitcnt lgkmcnt(0)
	s_barrier
	s_setprio 1
	v_mfma_f32_16x16x32_bf16 v[124:127], v[150:153], v[182:185], v[124:127]
	v_mfma_f32_16x16x32_bf16 v[120:123], v[158:161], v[182:185], v[120:123]
	v_mfma_f32_16x16x32_bf16 v[108:111], v[150:153], v[196:199], v[108:111]
	v_mfma_f32_16x16x32_bf16 v[104:107], v[158:161], v[196:199], v[104:107]
	v_mfma_f32_16x16x32_bf16 v[92:95], v[150:153], v[204:207], v[92:95]
	v_mfma_f32_16x16x32_bf16 v[88:91], v[158:161], v[204:207], v[88:91]
	v_mfma_f32_16x16x32_bf16 v[76:79], v[150:153], v[212:215], v[76:79]
	v_mfma_f32_16x16x32_bf16 v[72:75], v[158:161], v[212:215], v[72:75]
	v_mfma_f32_16x16x32_bf16 v[124:127], v[154:157], v[192:195], v[124:127]
	v_mfma_f32_16x16x32_bf16 v[120:123], v[162:165], v[192:195], v[120:123]
	v_mfma_f32_16x16x32_bf16 v[108:111], v[154:157], v[200:203], v[108:111]
	v_mfma_f32_16x16x32_bf16 v[104:107], v[162:165], v[200:203], v[104:107]
	v_mfma_f32_16x16x32_bf16 v[92:95], v[154:157], v[208:211], v[92:95]
	v_mfma_f32_16x16x32_bf16 v[88:91], v[162:165], v[208:211], v[88:91]
	v_mfma_f32_16x16x32_bf16 v[76:79], v[154:157], v[216:219], v[76:79]
	v_mfma_f32_16x16x32_bf16 v[72:75], v[162:165], v[216:219], v[72:75]
	v_mfma_f32_16x16x32_bf16 v[116:119], v[166:169], v[182:185], v[116:119]
	v_mfma_f32_16x16x32_bf16 v[112:115], v[174:177], v[182:185], v[112:115]
	v_mfma_f32_16x16x32_bf16 v[100:103], v[166:169], v[196:199], v[100:103]
	v_mfma_f32_16x16x32_bf16 v[96:99], v[174:177], v[196:199], v[96:99]
	v_mfma_f32_16x16x32_bf16 v[84:87], v[166:169], v[204:207], v[84:87]
	v_mfma_f32_16x16x32_bf16 v[80:83], v[174:177], v[204:207], v[80:83]
	v_mfma_f32_16x16x32_bf16 v[68:71], v[166:169], v[212:215], v[68:71]
	v_mfma_f32_16x16x32_bf16 v[64:67], v[174:177], v[212:215], v[64:67]
	v_mfma_f32_16x16x32_bf16 v[116:119], v[170:173], v[192:195], v[116:119]
	v_mfma_f32_16x16x32_bf16 v[112:115], v[178:181], v[192:195], v[112:115]
	v_mfma_f32_16x16x32_bf16 v[100:103], v[170:173], v[200:203], v[100:103]
	v_mfma_f32_16x16x32_bf16 v[96:99], v[178:181], v[200:203], v[96:99]
	v_mfma_f32_16x16x32_bf16 v[84:87], v[170:173], v[208:211], v[84:87]
	v_mfma_f32_16x16x32_bf16 v[80:83], v[178:181], v[208:211], v[80:83]
	v_mfma_f32_16x16x32_bf16 v[68:71], v[170:173], v[216:219], v[68:71]
	v_mfma_f32_16x16x32_bf16 v[64:67], v[178:181], v[216:219], v[64:67]
	s_setprio 0
	s_barrier
; #define PG8_STAGE(bufoff, gbase, voff) do { _Pragma("unroll") for (int _i = 0; _i < 2; ++_i) \
;         __builtin_amdgcn_global_load_lds((const unsigned*)((const char*)(gbase) + (voff)[_i]), (PG8_LAS unsigned*)(lds + (bufoff) + ldsw + _i * 8192), 16, 0, 0); } while (0)
; #define PG8_LDA(dst, b, h) do { _Pragma("unroll") for (int m = 0; m < 4; ++m) _Pragma("unroll") for (int k = 0; k < 2; ++k) dst[m][k] = *(const PG8_LAS bf16x8*)(lds + PG8_SA(b, h) + aoff + m * 2048 + k * 1024); } while (0)
; #define PG8_MMA(ai, bj, At, Bt) do { __builtin_amdgcn_s_setprio(1); _Pragma("unroll") for (int m = 0; m < 4; ++m) _Pragma("unroll") for (int n = 0; n < 2; ++n) _Pragma("unroll") for (int k = 0; k < 2; ++k) \
;         acc[ai][bj][m][n] = __builtin_amdgcn_mfma_f32_16x16x32_bf16(Bt[n][k], At[m][k], acc[ai][bj][m][n], 0, 0, 0); __builtin_amdgcn_s_setprio(0); } while (0)
; #define PG8_WAIT_V(n) asm volatile("s_waitcnt vmcnt(" #n ")" ::: "memory")
; #define PG8_WAIT_L(n) asm volatile("s_waitcnt lgkmcnt(" #n ")" ::: "memory")
; #define PG8_BAR __builtin_amdgcn_s_barrier()
; #define PG8_SCHED __builtin_amdgcn_sched_barrier(0)
; template <class Epi, class Sched, bool ALIGN_EPI = false, bool SP2 = false>
; __device__ __forceinline__ void gemm_phase(PG8_LAS unsigned char* lds, const Gemm g, const Sched& S, const Epi& E) {
;     ...
;             PG8_LDA(At, 1, 1); PG8_STAGE(PG8_SB(1, 0), b3, voffB); PG8_STAGE(PG8_SB(1, 1), b3 + hstep, voffB); PG8_STAGE(PG8_SA(1, 0), a3, voffA);
;             PG8_WAIT_V(8); PG8_WAIT_L(0); PG8_BAR; PG8_MMA(1, 0, At, B0); PG8_MMA(1, 1, At, B1); PG8_BAR; PG8_SCHED;
	s_add_i32 s30, s55, s35
	v_lshl_add_u64 v[186:187], v[186:187], 0, s[4:5]
	s_mov_b32 m0, s30
	ds_read_b128 v[182:185], v149 offset:49152
	ds_read_b128 v[192:195], v149 offset:50176
	ds_read_b128 v[196:199], v149 offset:51200
	ds_read_b128 v[200:203], v149 offset:52224
	ds_read_b128 v[204:207], v149 offset:53248
	ds_read_b128 v[208:211], v149 offset:54272
	ds_read_b128 v[212:215], v149 offset:55296
	ds_read_b128 v[216:219], v149 offset:56320
	global_load_lds_dwordx4 v[186:187], off
	s_add_i32 m0, s30, 0x2000
	s_add_u32 s24, s24, 0x40080
	v_lshl_add_u64 v[186:187], v[220:221], 0, s[4:5]
	s_addc_u32 s25, s25, 0
	s_add_i32 s30, s56, s35
	global_load_lds_dwordx4 v[186:187], off
	v_lshl_add_u64 v[186:187], s[24:25], 0, v[132:133]
	s_mov_b32 m0, s30
	s_nop 0
	global_load_lds_dwordx4 v[186:187], off
	v_lshl_add_u64 v[186:187], s[24:25], 0, v[128:129]
	s_add_i32 m0, s30, 0x2000
	s_nop 0
	global_load_lds_dwordx4 v[186:187], off
	v_lshl_add_u64 v[186:187], v[222:223], 0, s[4:5]
	s_mov_b32 m0, s42
	s_nop 0
	global_load_lds_dwordx4 v[186:187], off
	v_lshl_add_u64 v[186:187], v[224:225], 0, s[4:5]
	s_mov_b32 m0, s43
	s_nop 0
	global_load_lds_dwordx4 v[186:187], off
	s_waitcnt vmcnt(8)
	s_waitcnt lgkmcnt(0)
	s_barrier
	s_setprio 1
	v_mfma_f32_16x16x32_bf16 v[60:63], v[150:153], v[182:185], v[60:63]
	v_mfma_f32_16x16x32_bf16 v[56:59], v[158:161], v[182:185], v[56:59]
	v_mfma_f32_16x16x32_bf16 v[44:47], v[150:153], v[196:199], v[44:47]
	v_mfma_f32_16x16x32_bf16 v[40:43], v[158:161], v[196:199], v[40:43]
	v_mfma_f32_16x16x32_bf16 v[28:31], v[150:153], v[204:207], v[28:31]
	v_mfma_f32_16x16x32_bf16 v[24:27], v[158:161], v[204:207], v[24:27]
	v_mfma_f32_16x16x32_bf16 v[12:15], v[150:153], v[212:215], v[12:15]
	v_mfma_f32_16x16x32_bf16 v[8:11], v[158:161], v[212:215], v[8:11]
	v_mfma_f32_16x16x32_bf16 v[60:63], v[154:157], v[192:195], v[60:63]
	v_mfma_f32_16x16x32_bf16 v[56:59], v[162:165], v[192:195], v[56:59]
	v_mfma_f32_16x16x32_bf16 v[44:47], v[154:157], v[200:203], v[44:47]
	v_mfma_f32_16x16x32_bf16 v[40:43], v[162:165], v[200:203], v[40:43]
	v_mfma_f32_16x16x32_bf16 v[28:31], v[154:157], v[208:211], v[28:31]
	v_mfma_f32_16x16x32_bf16 v[24:27], v[162:165], v[208:211], v[24:27]
	v_mfma_f32_16x16x32_bf16 v[12:15], v[154:157], v[216:219], v[12:15]
	v_mfma_f32_16x16x32_bf16 v[8:11], v[162:165], v[216:219], v[8:11]
	v_mfma_f32_16x16x32_bf16 v[52:55], v[166:169], v[182:185], v[52:55]
	v_mfma_f32_16x16x32_bf16 v[48:51], v[174:177], v[182:185], v[48:51]
	v_mfma_f32_16x16x32_bf16 v[36:39], v[166:169], v[196:199], v[36:39]
	v_mfma_f32_16x16x32_bf16 v[32:35], v[174:177], v[196:199], v[32:35]
	v_mfma_f32_16x16x32_bf16 v[20:23], v[166:169], v[204:207], v[20:23]
	v_mfma_f32_16x16x32_bf16 v[16:19], v[174:177], v[204:207], v[16:19]
	v_mfma_f32_16x16x32_bf16 v[4:7], v[166:169], v[212:215], v[4:7]
	v_mfma_f32_16x16x32_bf16 v[0:3], v[174:177], v[212:215], v[0:3]
	v_mfma_f32_16x16x32_bf16 v[52:55], v[170:173], v[192:195], v[52:55]
	v_mfma_f32_16x16x32_bf16 v[48:51], v[178:181], v[192:195], v[48:51]
	v_mfma_f32_16x16x32_bf16 v[36:39], v[170:173], v[200:203], v[36:39]
	v_mfma_f32_16x16x32_bf16 v[32:35], v[178:181], v[200:203], v[32:35]
	v_mfma_f32_16x16x32_bf16 v[20:23], v[170:173], v[208:211], v[20:23]
	v_mfma_f32_16x16x32_bf16 v[16:19], v[178:181], v[208:211], v[16:19]
	v_mfma_f32_16x16x32_bf16 v[4:7], v[170:173], v[216:219], v[4:7]
	v_mfma_f32_16x16x32_bf16 v[0:3], v[178:181], v[216:219], v[0:3]
	s_setprio 0
	s_barrier
	s_add_i32 s54, s54, 2
	s_add_u32 s22, s22, 0x100
	s_addc_u32 s23, s23, 0
	s_add_u32 s52, s52, 0x100
	s_addc_u32 s53, s53, 0

; #define PG8_STAGE(bufoff, gbase, voff) do { _Pragma("unroll") for (int _i = 0; _i < 2; ++_i) \
;         __builtin_amdgcn_global_load_lds((const unsigned*)((const char*)(gbase) + (voff)[_i]), (PG8_LAS unsigned*)(lds + (bufoff) + ldsw + _i * 8192), 16, 0, 0); } while (0)
; #define PG8_WAIT_V(n) asm volatile("s_waitcnt vmcnt(" #n ")" ::: "memory")
; #define PG8_BAR __builtin_amdgcn_s_barrier()
; template <class Epi, class Sched, bool ALIGN_EPI = false, bool SP2 = false>
; __device__ __forceinline__ void gemm_phase(PG8_LAS unsigned char* lds, const Gemm g, const Sched& S, const Epi& E) {
;     ...
;     const int wid = __builtin_amdgcn_readfirstlane(tid >> 6), lane = tid & 63, wr = wid >> 2, wc = wid & 3, fr = lane & 15, fq = lane >> 4;
;     const int K = g.K, nt = K / BK;
;     unsigned voffA[2], voffB[2];
; #pragma unroll
;     for (int i = 0; i < 2; ++i) { int R, C; stage_rc(tid * 16 + i * 8192, R, C); const int Rb = Epi::PERM ? ((R & ~31) + perm32(R & 31)) : R;
;         voffA[i] = (unsigned)(R * K + C) * 2u; voffB[i] = (unsigned)(Rb * K + C) * 2u; }
;     const size_t kstep = (size_t)(BK * 2);
;     const size_t hstep = (size_t)HALF * K * 2;
;     const size_t tstep = 2 * hstep;
;     const unsigned ldsw = (unsigned)wid * 1024u;
;     const int aoff = lds_byte(wr * 64 + fr, fq * 8), boff = lds_byte(wc * 32 + fr, fq * 8);
;     ...
;         PG8_STAGE(PG8_SB(0, 0), cB, voffB); PG8_STAGE(PG8_SB(0, 1), cB + hstep, voffB); PG8_STAGE(PG8_SA(0, 0), cA, voffA); PG8_STAGE(PG8_SA(0, 1), cA + hstep, voffA);
;         if (wr == 1) PG8_BAR;
;         PG8_WAIT_V(2); PG8_BAR;
;         PG8_STAGE(PG8_SB(1, 0), cB + kstep, voffB); PG8_STAGE(PG8_SA(1, 0), cA + kstep, voffA); PG8_STAGE(PG8_SB(1, 1), cB + hstep + kstep, voffB);
;         PG8_WAIT_V(6); PG8_BAR;
.LBB0_776:
	s_lshl_b32 s1, s6, 5
	s_mov_b64 s[6:7], 0x80
	s_and_b32 s16, s1, 0x60
	s_add_i32 m0, s34, 0x18000
	v_lshl_add_u64 v[6:7], v[6:7], 0, s[6:7]
	s_lshl_b32 s13, s12, 13
	s_lshl_b32 s17, s16, 7
	s_waitcnt vmcnt(2)
	s_barrier
	global_load_lds_dwordx4 v[6:7], off
	v_lshl_add_u64 v[4:5], v[4:5], 0, s[6:7]
	s_add_i32 m0, s34, 0x1a000
	s_add_i32 s39, s34, 0x8000
	s_add_i32 s40, s34, 0xa000
	global_load_lds_dwordx4 v[4:5], off
	v_lshl_add_u64 v[0:1], v[0:1], 0, s[6:7]
	s_mov_b32 m0, s39
	s_add_u32 s14, s24, 0x40080
	global_load_lds_dwordx4 v[0:1], off
	v_lshl_add_u64 v[0:1], v[2:3], 0, s[6:7]
	s_mov_b32 m0, s40
	s_addc_u32 s15, s25, 0
	global_load_lds_dwordx4 v[0:1], off
	s_add_i32 m0, s34, 0x1c000
	v_lshl_add_u64 v[0:1], s[14:15], 0, v[132:133]
	global_load_lds_dwordx4 v[0:1], off
	v_lshl_add_u64 v[0:1], s[14:15], 0, v[128:129]
	s_add_i32 m0, s34, 0x1e000
	s_cmpk_lt_u32 s5, 0x100
	global_load_lds_dwordx4 v[0:1], off
	v_lshrrev_b32_e32 v1, 1, v9
	v_and_b32_e32 v1, 24, v1
	v_and_b32_e32 v0, 15, v9
	v_lshlrev_b32_e32 v2, 1, v1
	v_lshl_or_b32 v148, s12, 6, v0
	v_lshl_or_b32 v0, v0, 6, v2
	v_lshlrev_b32_e32 v2, 2, v9
	v_and_b32_e32 v2, 32, v2
	v_bitop3_b32 v3, v0, s13, v2 bitop3:0xde
	v_bitop3_b32 v149, v0, s17, v2 bitop3:0xde
	v_lshlrev_b32_e32 v0, 14, v13
	v_and_b32_e32 v0, 0xffff8000, v0
	v_or_b32_e32 v150, s16, v1
	v_lshl_add_u32 v0, v12, 11, v0
	v_and_b32_e32 v1, 1, v13
	v_lshl_or_b32 v0, v1, 6, v0
	v_lshl_add_u32 v136, v14, 1, v0
	v_lshlrev_b32_e32 v0, 14, v8
	v_and_b32_e32 v0, 0xffff8000, v0
	s_waitcnt vmcnt(0)
	v_lshl_add_u32 v0, v10, 11, v0
	v_and_b32_e32 v1, 1, v8
	s_sext_i32_i8 s1, s4
	s_cselect_b64 s[12:13], -1, 0
	v_readlane_b32 s4, v235, 6
	v_lshl_or_b32 v0, v1, 6, v0
	s_add_i32 s43, 0, 0x10000
	s_add_i32 s44, 0, 0x14000
	s_ashr_i32 s41, s4, 31
	s_mov_b32 s42, s4
	v_mov_b32_e32 v137, v133
	v_lshl_add_u32 v138, v11, 1, v0
	v_mov_b32_e32 v139, v133
	v_mov_b64_e32 v[140:141], 0xb00
	v_mov_b64_e32 v[142:143], 0xaff
	v_add_u32_e32 v151, s43, v149
	v_add_u32_e32 v152, s44, v149
	v_add_u32_e32 v153, 0, v3
	v_mov_b32_e32 v154, 0x358637bd
	s_mov_b32 s45, 0x800000
	s_movk_i32 s46, 0x1600
	s_barrier
	v_readlane_b32 s5, v235, 7
	s_branch .LBB0_779

; #define PG8_STAGE(bufoff, gbase, voff) do { _Pragma("unroll") for (int _i = 0; _i < 2; ++_i) \
;         __builtin_amdgcn_global_load_lds((const unsigned*)((const char*)(gbase) + (voff)[_i]), (PG8_LAS unsigned*)(lds + (bufoff) + ldsw + _i * 8192), 16, 0, 0); } while (0)
; #define PG8_LDA(dst, b, h) do { _Pragma("unroll") for (int m = 0; m < 4; ++m) _Pragma("unroll") for (int k = 0; k < 2; ++k) dst[m][k] = *(const PG8_LAS bf16x8*)(lds + PG8_SA(b, h) + aoff + m * 2048 + k * 1024); } while (0)
; #define PG8_LDB(dst, b, h) do { _Pragma("unroll") for (int n = 0; n < 2; ++n) _Pragma("unroll") for (int k = 0; k < 2; ++k) dst[n][k] = *(const PG8_LAS bf16x8*)(lds + PG8_SB(b, h) + boff + n * 2048 + k * 1024); } while (0)
; #define PG8_WAIT_V(n) asm volatile("s_waitcnt vmcnt(" #n ")" ::: "memory")
; #define PG8_WAIT_L(n) asm volatile("s_waitcnt lgkmcnt(" #n ")" ::: "memory")
; #define PG8_BAR __builtin_amdgcn_s_barrier()
; #define PG8_SCHED __builtin_amdgcn_sched_barrier(0)
; template <class Epi, class Sched, bool ALIGN_EPI = false, bool SP2 = false>
; __device__ __forceinline__ void gemm_phase(PG8_LAS unsigned char* lds, const Gemm g, const Sched& S, const Epi& E) {
;     ...
;         const bool has_next = S.next(ui + 1, nxt);
;         const char* nA = has_next ? (const char*)g.A + (size_t)nxt.pm * tstep : cA; const char* nB = has_next ? (const char*)g.Bt + (size_t)nxt.pn * tstep : cB;
;         for (int t = 0; t < nt; t += 2) {
;             const bool last = (t == nt - 2);
;             const char* a1 = cA + (size_t)(t + 1) * kstep;
;             const char* a2 = last ? nA : cA + (size_t)(t + 2) * kstep; const char* b2 = last ? nB : cB + (size_t)(t + 2) * kstep;
;             const char* a3 = a2 + kstep; const char* b3 = b2 + kstep;
;             if (last && has_next) S.a_ready(nxt);
;             if constexpr (SP2) {
;             PG8_LDB(B0, 0, 0); PG8_LDB(B1, 0, 1); PG8_SCHED; PG8_LDA(At, 0, 0); PG8_STAGE(PG8_SA(1, 1), a1 + hstep, voffA);
;             PG8_WAIT_V(8); PG8_WAIT_L(0); PG8_BAR; PG8_MMA(0, 0, At, B0); PG8_MMA(0, 1, At, B1); PG8_BAR; PG8_SCHED;
;             PG8_LDA(At, 0, 1); PG8_STAGE(PG8_SB(0, 0), b2, voffB); PG8_STAGE(PG8_SB(0, 1), b2 + hstep, voffB); PG8_STAGE(PG8_SA(0, 0), a2, voffA);
;             PG8_WAIT_V(8); PG8_WAIT_L(0); PG8_BAR; PG8_MMA(1, 0, At, B0); PG8_MMA(1, 1, At, B1); PG8_BAR; PG8_SCHED;
.LBB0_781:
	s_ashr_i32 s17, s16, 31
	s_lshl_b64 s[18:19], s[16:17], 19
	s_add_u32 s18, s8, s18
	s_addc_u32 s19, s9, s19
	s_and_b64 s[20:21], s[4:5], exec
	s_cselect_b32 s17, s19, s23
	s_cselect_b32 s47, s18, s22
	s_ashr_i32 s15, s14, 31
	s_lshl_b64 s[20:21], s[14:15], 19
	s_add_u32 s20, s28, s20
	s_addc_u32 s21, s29, s21
	s_and_b64 s[26:27], s[4:5], exec
	s_cselect_b32 s15, s21, s25
	s_cselect_b32 s48, s20, s24
	s_add_u32 s22, s22, 0x40080
	s_addc_u32 s23, s23, 0
	s_add_u32 s49, s24, 0x100
	s_addc_u32 s50, s25, 0
	s_mov_b32 s51, -2
	ds_read_b128 v[144:147], v151
	ds_read_b128 v[156:159], v151 offset:1024
	ds_read_b128 v[160:163], v151 offset:2048
	ds_read_b128 v[164:167], v151 offset:3072
	ds_read_b128 v[168:171], v152
	ds_read_b128 v[172:175], v152 offset:1024
	ds_read_b128 v[176:179], v152 offset:2048
	ds_read_b128 v[180:183], v152 offset:3072
	s_add_u32 s24, s22, 0xfffc0080
	s_addc_u32 s25, s23, -1
	s_cmp_eq_u32 s51, 12
	s_cselect_b32 s27, s17, s25
	s_cselect_b32 s26, s47, s24
	s_cselect_b32 s25, s15, s50
	s_cselect_b32 s24, s48, s49
	v_lshl_add_u64 v[218:219], s[22:23], 0, v[136:137]
	s_add_i32 m0, s34, 0xc000
	ds_read_b128 v[184:187], v153
	ds_read_b128 v[190:193], v153 offset:1024
	ds_read_b128 v[194:197], v153 offset:2048
	ds_read_b128 v[198:201], v153 offset:3072
	ds_read_b128 v[202:205], v153 offset:4096
	ds_read_b128 v[206:209], v153 offset:5120
	ds_read_b128 v[210:213], v153 offset:6144
	ds_read_b128 v[214:217], v153 offset:7168
	global_load_lds_dwordx4 v[218:219], off
	v_lshl_add_u64 v[218:219], s[22:23], 0, v[138:139]
	s_add_i32 m0, s34, 0xe000
	s_nop 0
	global_load_lds_dwordx4 v[218:219], off
	s_waitcnt vmcnt(16)
	s_waitcnt lgkmcnt(0)
	s_barrier
	s_setprio 1
	v_mfma_f32_16x16x32_bf16 v[116:119], v[144:147], v[184:187], 0
	v_mfma_f32_16x16x32_bf16 v[112:115], v[160:163], v[184:187], 0
	v_mfma_f32_16x16x32_bf16 v[100:103], v[144:147], v[194:197], 0
	v_mfma_f32_16x16x32_bf16 v[96:99], v[160:163], v[194:197], 0
	v_mfma_f32_16x16x32_bf16 v[84:87], v[144:147], v[202:205], 0
	v_mfma_f32_16x16x32_bf16 v[80:83], v[160:163], v[202:205], 0
	v_mfma_f32_16x16x32_bf16 v[72:75], v[144:147], v[210:213], 0
	v_mfma_f32_16x16x32_bf16 v[64:67], v[160:163], v[210:213], 0
	v_mfma_f32_16x16x32_bf16 v[116:119], v[156:159], v[190:193], v[116:119]
	v_mfma_f32_16x16x32_bf16 v[112:115], v[164:167], v[190:193], v[112:115]
	v_mfma_f32_16x16x32_bf16 v[100:103], v[156:159], v[198:201], v[100:103]
	v_mfma_f32_16x16x32_bf16 v[96:99], v[164:167], v[198:201], v[96:99]
	v_mfma_f32_16x16x32_bf16 v[84:87], v[156:159], v[206:209], v[84:87]
	v_mfma_f32_16x16x32_bf16 v[80:83], v[164:167], v[206:209], v[80:83]
	v_mfma_f32_16x16x32_bf16 v[72:75], v[156:159], v[214:217], v[72:75]
	v_mfma_f32_16x16x32_bf16 v[64:67], v[164:167], v[214:217], v[64:67]
	v_mfma_f32_16x16x32_bf16 v[124:127], v[168:171], v[184:187], 0
	v_mfma_f32_16x16x32_bf16 v[120:123], v[176:179], v[184:187], 0
	v_mfma_f32_16x16x32_bf16 v[108:111], v[168:171], v[194:197], 0
	v_mfma_f32_16x16x32_bf16 v[104:107], v[176:179], v[194:197], 0
	v_mfma_f32_16x16x32_bf16 v[92:95], v[168:171], v[202:205], 0
	v_mfma_f32_16x16x32_bf16 v[88:91], v[176:179], v[202:205], 0
	v_mfma_f32_16x16x32_bf16 v[76:79], v[168:171], v[210:213], 0
	v_mfma_f32_16x16x32_bf16 v[68:71], v[176:179], v[210:213], 0
	v_mfma_f32_16x16x32_bf16 v[124:127], v[172:175], v[190:193], v[124:127]
	v_mfma_f32_16x16x32_bf16 v[120:123], v[180:183], v[190:193], v[120:123]
	v_mfma_f32_16x16x32_bf16 v[108:111], v[172:175], v[198:201], v[108:111]
	v_mfma_f32_16x16x32_bf16 v[104:107], v[180:183], v[198:201], v[104:107]
	v_mfma_f32_16x16x32_bf16 v[92:95], v[172:175], v[206:209], v[92:95]
	v_mfma_f32_16x16x32_bf16 v[88:91], v[180:183], v[206:209], v[88:91]
	v_mfma_f32_16x16x32_bf16 v[76:79], v[172:175], v[214:217], v[76:79]
	v_mfma_f32_16x16x32_bf16 v[68:71], v[180:183], v[214:217], v[68:71]
	s_setprio 0
	s_barrier
	s_add_i32 s52, s43, s30
	v_lshl_add_u64 v[218:219], s[24:25], 0, v[132:133]
	s_mov_b32 m0, s52
	ds_read_b128 v[184:187], v153 offset:16384
	ds_read_b128 v[190:193], v153 offset:17408
	ds_read_b128 v[194:197], v153 offset:18432
	ds_read_b128 v[198:201], v153 offset:19456
	ds_read_b128 v[202:205], v153 offset:20480
	ds_read_b128 v[206:209], v153 offset:21504
	ds_read_b128 v[210:213], v153 offset:22528
	ds_read_b128 v[214:217], v153 offset:23552
	global_load_lds_dwordx4 v[218:219], off
	s_add_i32 m0, s52, 0x2000
	s_add_u32 s52, s24, 0x40000
	v_lshl_add_u64 v[220:221], s[24:25], 0, v[128:129]
	s_addc_u32 s53, s25, 0
	s_add_i32 s54, s44, s30
	global_load_lds_dwordx4 v[220:221], off
	v_lshl_add_u64 v[222:223], s[52:53], 0, v[132:133]
	s_mov_b32 m0, s54
	v_lshl_add_u64 v[224:225], s[26:27], 0, v[130:131]
	global_load_lds_dwordx4 v[222:223], off
	v_lshl_add_u64 v[222:223], s[52:53], 0, v[128:129]
	s_add_i32 m0, s54, 0x2000
	s_nop 0
	global_load_lds_dwordx4 v[222:223], off
	v_lshl_add_u64 v[222:223], s[26:27], 0, v[134:135]
	s_mov_b32 m0, s34
	s_nop 0
	global_load_lds_dwordx4 v[222:223], off
	s_mov_b32 m0, s35
	s_nop 0
	global_load_lds_dwordx4 v[224:225], off
	s_waitcnt vmcnt(16)
	s_waitcnt lgkmcnt(0)
	s_barrier
; #define PG8_STAGE(bufoff, gbase, voff) do { _Pragma("unroll") for (int _i = 0; _i < 2; ++_i) \
;         __builtin_amdgcn_global_load_lds((const unsigned*)((const char*)(gbase) + (voff)[_i]), (PG8_LAS unsigned*)(lds + (bufoff) + ldsw + _i * 8192), 16, 0, 0); } while (0)
; #define PG8_LDA(dst, b, h) do { _Pragma("unroll") for (int m = 0; m < 4; ++m) _Pragma("unroll") for (int k = 0; k < 2; ++k) dst[m][k] = *(const PG8_LAS bf16x8*)(lds + PG8_SA(b, h) + aoff + m * 2048 + k * 1024); } while (0)
; #define PG8_LDB(dst, b, h) do { _Pragma("unroll") for (int n = 0; n < 2; ++n) _Pragma("unroll") for (int k = 0; k < 2; ++k) dst[n][k] = *(const PG8_LAS bf16x8*)(lds + PG8_SB(b, h) + boff + n * 2048 + k * 1024); } while (0)
; #define PG8_MMA(ai, bj, At, Bt) do { __builtin_amdgcn_s_setprio(1); _Pragma("unroll") for (int m = 0; m < 4; ++m) _Pragma("unroll") for (int n = 0; n < 2; ++n) _Pragma("unroll") for (int k = 0; k < 2; ++k) \
;         acc[ai][bj][m][n] = __builtin_amdgcn_mfma_f32_16x16x32_bf16(Bt[n][k], At[m][k], acc[ai][bj][m][n], 0, 0, 0); __builtin_amdgcn_s_setprio(0); } while (0)
; #define PG8_WAIT_V(n) asm volatile("s_waitcnt vmcnt(" #n ")" ::: "memory")
; #define PG8_WAIT_L(n) asm volatile("s_waitcnt lgkmcnt(" #n ")" ::: "memory")
; #define PG8_BAR __builtin_amdgcn_s_barrier()
; #define PG8_SCHED __builtin_amdgcn_sched_barrier(0)
; template <class Epi, class Sched, bool ALIGN_EPI = false, bool SP2 = false>
; __device__ __forceinline__ void gemm_phase(PG8_LAS unsigned char* lds, const Gemm g, const Sched& S, const Epi& E) {
;     ...
;             PG8_LDA(At, 0, 1); PG8_STAGE(PG8_SB(0, 0), b2, voffB); PG8_STAGE(PG8_SB(0, 1), b2 + hstep, voffB); PG8_STAGE(PG8_SA(0, 0), a2, voffA);
;             PG8_WAIT_V(8); PG8_WAIT_L(0); PG8_BAR; PG8_MMA(1, 0, At, B0); PG8_MMA(1, 1, At, B1); PG8_BAR; PG8_SCHED;
;             PG8_LDB(B0, 1, 0); PG8_LDB(B1, 1, 1); PG8_SCHED; PG8_LDA(At, 1, 0); PG8_STAGE(PG8_SA(0, 1), a2 + hstep, voffA);
;             PG8_WAIT_V(8); PG8_WAIT_L(0); PG8_BAR; PG8_MMA(0, 0, At, B0); PG8_MMA(0, 1, At, B1); PG8_BAR; PG8_SCHED;
	s_setprio 1
	v_mfma_f32_16x16x32_bf16 v[56:59], v[144:147], v[184:187], 0
	v_mfma_f32_16x16x32_bf16 v[48:51], v[160:163], v[184:187], 0
	v_mfma_f32_16x16x32_bf16 v[40:43], v[144:147], v[194:197], 0
	v_mfma_f32_16x16x32_bf16 v[32:35], v[160:163], v[194:197], 0
	v_mfma_f32_16x16x32_bf16 v[24:27], v[144:147], v[202:205], 0
	v_mfma_f32_16x16x32_bf16 v[16:19], v[160:163], v[202:205], 0
	v_mfma_f32_16x16x32_bf16 v[8:11], v[144:147], v[210:213], 0
	v_mfma_f32_16x16x32_bf16 v[0:3], v[160:163], v[210:213], 0
	v_mfma_f32_16x16x32_bf16 v[56:59], v[156:159], v[190:193], v[56:59]
	v_mfma_f32_16x16x32_bf16 v[48:51], v[164:167], v[190:193], v[48:51]
	v_mfma_f32_16x16x32_bf16 v[40:43], v[156:159], v[198:201], v[40:43]
	v_mfma_f32_16x16x32_bf16 v[32:35], v[164:167], v[198:201], v[32:35]
	v_mfma_f32_16x16x32_bf16 v[24:27], v[156:159], v[206:209], v[24:27]
	v_mfma_f32_16x16x32_bf16 v[16:19], v[164:167], v[206:209], v[16:19]
	v_mfma_f32_16x16x32_bf16 v[8:11], v[156:159], v[214:217], v[8:11]
	v_mfma_f32_16x16x32_bf16 v[0:3], v[164:167], v[214:217], v[0:3]
	v_mfma_f32_16x16x32_bf16 v[60:63], v[168:171], v[184:187], 0
	v_mfma_f32_16x16x32_bf16 v[52:55], v[176:179], v[184:187], 0
	v_mfma_f32_16x16x32_bf16 v[44:47], v[168:171], v[194:197], 0
	v_mfma_f32_16x16x32_bf16 v[36:39], v[176:179], v[194:197], 0
	v_mfma_f32_16x16x32_bf16 v[28:31], v[168:171], v[202:205], 0
	v_mfma_f32_16x16x32_bf16 v[20:23], v[176:179], v[202:205], 0
	v_mfma_f32_16x16x32_bf16 v[12:15], v[168:171], v[210:213], 0
	v_mfma_f32_16x16x32_bf16 v[4:7], v[176:179], v[210:213], 0
	v_mfma_f32_16x16x32_bf16 v[60:63], v[172:175], v[190:193], v[60:63]
	v_mfma_f32_16x16x32_bf16 v[52:55], v[180:183], v[190:193], v[52:55]
	v_mfma_f32_16x16x32_bf16 v[44:47], v[172:175], v[198:201], v[44:47]
	v_mfma_f32_16x16x32_bf16 v[36:39], v[180:183], v[198:201], v[36:39]
	v_mfma_f32_16x16x32_bf16 v[28:31], v[172:175], v[206:209], v[28:31]
	v_mfma_f32_16x16x32_bf16 v[20:23], v[180:183], v[206:209], v[20:23]
	v_mfma_f32_16x16x32_bf16 v[12:15], v[172:175], v[214:217], v[12:15]
	v_mfma_f32_16x16x32_bf16 v[4:7], v[180:183], v[214:217], v[4:7]
	s_setprio 0
	s_barrier
	s_add_i32 s52, 0, 0x18000
	v_add_u32_e32 v155, s52, v149
	s_add_i32 s53, 0, 0x1c000
	ds_read_b128 v[144:147], v155
	ds_read_b128 v[156:159], v155 offset:1024
	ds_read_b128 v[160:163], v155 offset:2048
	ds_read_b128 v[164:167], v155 offset:3072
	v_add_u32_e32 v155, s53, v149
	ds_read_b128 v[168:171], v155
	ds_read_b128 v[172:175], v155 offset:1024
	ds_read_b128 v[176:179], v155 offset:2048
	ds_read_b128 v[180:183], v155 offset:3072
	s_add_u32 s26, s26, 0x40000
	s_addc_u32 s27, s27, 0
	s_mov_b32 m0, s36
	v_lshl_add_u64 v[226:227], s[26:27], 0, v[134:135]
	ds_read_b128 v[184:187], v153 offset:32768
	ds_read_b128 v[190:193], v153 offset:33792
	ds_read_b128 v[194:197], v153 offset:34816
	ds_read_b128 v[198:201], v153 offset:35840
	ds_read_b128 v[202:205], v153 offset:36864
	ds_read_b128 v[206:209], v153 offset:37888
	ds_read_b128 v[210:213], v153 offset:38912
	ds_read_b128 v[214:217], v153 offset:39936
	global_load_lds_dwordx4 v[226:227], off
	v_lshl_add_u64 v[226:227], s[26:27], 0, v[130:131]
	s_mov_b32 m0, s37
	s_nop 0
	global_load_lds_dwordx4 v[226:227], off
	s_waitcnt vmcnt(8)
	s_waitcnt lgkmcnt(0)
	s_barrier
	s_setprio 1
	v_mfma_f32_16x16x32_bf16 v[116:119], v[144:147], v[184:187], v[116:119]
	v_mfma_f32_16x16x32_bf16 v[112:115], v[160:163], v[184:187], v[112:115]
	v_mfma_f32_16x16x32_bf16 v[100:103], v[144:147], v[194:197], v[100:103]
	v_mfma_f32_16x16x32_bf16 v[96:99], v[160:163], v[194:197], v[96:99]
	v_mfma_f32_16x16x32_bf16 v[84:87], v[144:147], v[202:205], v[84:87]
	v_mfma_f32_16x16x32_bf16 v[80:83], v[160:163], v[202:205], v[80:83]
	v_mfma_f32_16x16x32_bf16 v[72:75], v[144:147], v[210:213], v[72:75]
	v_mfma_f32_16x16x32_bf16 v[64:67], v[160:163], v[210:213], v[64:67]
	v_mfma_f32_16x16x32_bf16 v[116:119], v[156:159], v[190:193], v[116:119]
	v_mfma_f32_16x16x32_bf16 v[112:115], v[164:167], v[190:193], v[112:115]
	v_mfma_f32_16x16x32_bf16 v[100:103], v[156:159], v[198:201], v[100:103]
	v_mfma_f32_16x16x32_bf16 v[96:99], v[164:167], v[198:201], v[96:99]
	v_mfma_f32_16x16x32_bf16 v[84:87], v[156:159], v[206:209], v[84:87]
	v_mfma_f32_16x16x32_bf16 v[80:83], v[164:167], v[206:209], v[80:83]
	v_mfma_f32_16x16x32_bf16 v[72:75], v[156:159], v[214:217], v[72:75]
	v_mfma_f32_16x16x32_bf16 v[64:67], v[164:167], v[214:217], v[64:67]
	v_mfma_f32_16x16x32_bf16 v[124:127], v[168:171], v[184:187], v[124:127]
	v_mfma_f32_16x16x32_bf16 v[120:123], v[176:179], v[184:187], v[120:123]
	v_mfma_f32_16x16x32_bf16 v[108:111], v[168:171], v[194:197], v[108:111]
	v_mfma_f32_16x16x32_bf16 v[104:107], v[176:179], v[194:197], v[104:107]
	v_mfma_f32_16x16x32_bf16 v[92:95], v[168:171], v[202:205], v[92:95]
	v_mfma_f32_16x16x32_bf16 v[88:91], v[176:179], v[202:205], v[88:91]
	v_mfma_f32_16x16x32_bf16 v[76:79], v[168:171], v[210:213], v[76:79]
	v_mfma_f32_16x16x32_bf16 v[68:71], v[176:179], v[210:213], v[68:71]
	v_mfma_f32_16x16x32_bf16 v[124:127], v[172:175], v[190:193], v[124:127]
	v_mfma_f32_16x16x32_bf16 v[120:123], v[180:183], v[190:193], v[120:123]
	v_mfma_f32_16x16x32_bf16 v[108:111], v[172:175], v[198:201], v[108:111]
	v_mfma_f32_16x16x32_bf16 v[104:107], v[180:183], v[198:201], v[104:107]
	v_mfma_f32_16x16x32_bf16 v[92:95], v[172:175], v[206:209], v[92:95]
	v_mfma_f32_16x16x32_bf16 v[88:91], v[180:183], v[206:209], v[88:91]
	v_mfma_f32_16x16x32_bf16 v[76:79], v[172:175], v[214:217], v[76:79]
	v_mfma_f32_16x16x32_bf16 v[68:71], v[180:183], v[214:217], v[68:71]
	s_setprio 0
	s_barrier
; #define PG8_STAGE(bufoff, gbase, voff) do { _Pragma("unroll") for (int _i = 0; _i < 2; ++_i) \
;         __builtin_amdgcn_global_load_lds((const unsigned*)((const char*)(gbase) + (voff)[_i]), (PG8_LAS unsigned*)(lds + (bufoff) + ldsw + _i * 8192), 16, 0, 0); } while (0)
; #define PG8_LDA(dst, b, h) do { _Pragma("unroll") for (int m = 0; m < 4; ++m) _Pragma("unroll") for (int k = 0; k < 2; ++k) dst[m][k] = *(const PG8_LAS bf16x8*)(lds + PG8_SA(b, h) + aoff + m * 2048 + k * 1024); } while (0)
; #define PG8_MMA(ai, bj, At, Bt) do { __builtin_amdgcn_s_setprio(1); _Pragma("unroll") for (int m = 0; m < 4; ++m) _Pragma("unroll") for (int n = 0; n < 2; ++n) _Pragma("unroll") for (int k = 0; k < 2; ++k) \
;         acc[ai][bj][m][n] = __builtin_amdgcn_mfma_f32_16x16x32_bf16(Bt[n][k], At[m][k], acc[ai][bj][m][n], 0, 0, 0); __builtin_amdgcn_s_setprio(0); } while (0)
; #define PG8_WAIT_V(n) asm volatile("s_waitcnt vmcnt(" #n ")" ::: "memory")
; #define PG8_WAIT_L(n) asm volatile("s_waitcnt lgkmcnt(" #n ")" ::: "memory")
; #define PG8_BAR __builtin_amdgcn_s_barrier()
; #define PG8_SCHED __builtin_amdgcn_sched_barrier(0)
; template <class Epi, class Sched, bool ALIGN_EPI = false, bool SP2 = false>
; __device__ __forceinline__ void gemm_phase(PG8_LAS unsigned char* lds, const Gemm g, const Sched& S, const Epi& E) {
;     ...
;             PG8_LDA(At, 1, 1); PG8_STAGE(PG8_SB(1, 0), b3, voffB); PG8_STAGE(PG8_SB(1, 1), b3 + hstep, voffB); PG8_STAGE(PG8_SA(1, 0), a3, voffA);
;             PG8_WAIT_V(8); PG8_WAIT_L(0); PG8_BAR; PG8_MMA(1, 0, At, B0); PG8_MMA(1, 1, At, B1); PG8_BAR; PG8_SCHED;
	s_add_i32 s26, s52, s30
	v_lshl_add_u64 v[218:219], v[218:219], 0, s[6:7]
	s_mov_b32 m0, s26
	ds_read_b128 v[184:187], v153 offset:49152
	ds_read_b128 v[190:193], v153 offset:50176
	ds_read_b128 v[194:197], v153 offset:51200
	ds_read_b128 v[198:201], v153 offset:52224
	ds_read_b128 v[202:205], v153 offset:53248
	ds_read_b128 v[206:209], v153 offset:54272
	ds_read_b128 v[210:213], v153 offset:55296
	ds_read_b128 v[214:217], v153 offset:56320
	global_load_lds_dwordx4 v[218:219], off
	s_add_i32 m0, s26, 0x2000
	s_add_u32 s24, s24, 0x40080
	v_lshl_add_u64 v[218:219], v[220:221], 0, s[6:7]
	s_addc_u32 s25, s25, 0
	s_add_i32 s26, s53, s30
	global_load_lds_dwordx4 v[218:219], off
	v_lshl_add_u64 v[218:219], s[24:25], 0, v[132:133]
	s_mov_b32 m0, s26
	s_nop 0
	global_load_lds_dwordx4 v[218:219], off
	v_lshl_add_u64 v[218:219], s[24:25], 0, v[128:129]
	s_add_i32 m0, s26, 0x2000
	s_nop 0
	global_load_lds_dwordx4 v[218:219], off
	v_lshl_add_u64 v[218:219], v[222:223], 0, s[6:7]
	s_mov_b32 m0, s39
	s_nop 0
	global_load_lds_dwordx4 v[218:219], off
	v_lshl_add_u64 v[218:219], v[224:225], 0, s[6:7]
	s_mov_b32 m0, s40
	s_nop 0
	global_load_lds_dwordx4 v[218:219], off
	s_waitcnt vmcnt(8)
	s_waitcnt lgkmcnt(0)
	s_barrier
	s_setprio 1
	v_mfma_f32_16x16x32_bf16 v[56:59], v[144:147], v[184:187], v[56:59]
	v_mfma_f32_16x16x32_bf16 v[48:51], v[160:163], v[184:187], v[48:51]
	v_mfma_f32_16x16x32_bf16 v[40:43], v[144:147], v[194:197], v[40:43]
	v_mfma_f32_16x16x32_bf16 v[32:35], v[160:163], v[194:197], v[32:35]
	v_mfma_f32_16x16x32_bf16 v[24:27], v[144:147], v[202:205], v[24:27]
	v_mfma_f32_16x16x32_bf16 v[16:19], v[160:163], v[202:205], v[16:19]
	v_mfma_f32_16x16x32_bf16 v[8:11], v[144:147], v[210:213], v[8:11]
	v_mfma_f32_16x16x32_bf16 v[0:3], v[160:163], v[210:213], v[0:3]
	v_mfma_f32_16x16x32_bf16 v[56:59], v[156:159], v[190:193], v[56:59]
	v_mfma_f32_16x16x32_bf16 v[48:51], v[164:167], v[190:193], v[48:51]
	v_mfma_f32_16x16x32_bf16 v[40:43], v[156:159], v[198:201], v[40:43]
	v_mfma_f32_16x16x32_bf16 v[32:35], v[164:167], v[198:201], v[32:35]
	v_mfma_f32_16x16x32_bf16 v[24:27], v[156:159], v[206:209], v[24:27]
	v_mfma_f32_16x16x32_bf16 v[16:19], v[164:167], v[206:209], v[16:19]
	v_mfma_f32_16x16x32_bf16 v[8:11], v[156:159], v[214:217], v[8:11]
	v_mfma_f32_16x16x32_bf16 v[0:3], v[164:167], v[214:217], v[0:3]
	v_mfma_f32_16x16x32_bf16 v[60:63], v[168:171], v[184:187], v[60:63]
	v_mfma_f32_16x16x32_bf16 v[52:55], v[176:179], v[184:187], v[52:55]
	v_mfma_f32_16x16x32_bf16 v[44:47], v[168:171], v[194:197], v[44:47]
	v_mfma_f32_16x16x32_bf16 v[36:39], v[176:179], v[194:197], v[36:39]
	v_mfma_f32_16x16x32_bf16 v[28:31], v[168:171], v[202:205], v[28:31]
	v_mfma_f32_16x16x32_bf16 v[20:23], v[176:179], v[202:205], v[20:23]
	v_mfma_f32_16x16x32_bf16 v[12:15], v[168:171], v[210:213], v[12:15]
	v_mfma_f32_16x16x32_bf16 v[4:7], v[176:179], v[210:213], v[4:7]
	v_mfma_f32_16x16x32_bf16 v[60:63], v[172:175], v[190:193], v[60:63]
	v_mfma_f32_16x16x32_bf16 v[52:55], v[180:183], v[190:193], v[52:55]
	v_mfma_f32_16x16x32_bf16 v[44:47], v[172:175], v[198:201], v[44:47]
	v_mfma_f32_16x16x32_bf16 v[36:39], v[180:183], v[198:201], v[36:39]
	v_mfma_f32_16x16x32_bf16 v[28:31], v[172:175], v[206:209], v[28:31]
	v_mfma_f32_16x16x32_bf16 v[20:23], v[180:183], v[206:209], v[20:23]
	v_mfma_f32_16x16x32_bf16 v[12:15], v[172:175], v[214:217], v[12:15]
	v_mfma_f32_16x16x32_bf16 v[4:7], v[180:183], v[214:217], v[4:7]
	s_setprio 0
	s_barrier
	s_add_i32 s51, s51, 2
	s_add_u32 s22, s22, 0x100
	s_addc_u32 s23, s23, 0
	s_add_u32 s49, s49, 0x100
	s_addc_u32 s50, s50, 0
